# v85 + HGRN2: next chunk's q/k row loads issued row by row right after step 2 unpacks the current values; end-of-step burst keeps only the two v loads
# speedup vs baseline: 1.0189x; 1.0049x over previous
.LBB0_1169:
	s_waitcnt vmcnt(5)
	v_pk_add_f32 v[118:119], v[92:93], 0 op_sel_hi:[1,0]
	v_add_u32_e32 v58, s18, v132
	v_pk_add_f32 v[116:117], v[118:119], v[80:81]
	v_add_u32_e32 v160, 0, v132
	v_pk_add_f32 v[114:115], v[116:117], v[82:83]
	v_readlane_b32 s6, v254, 20
	v_pk_add_f32 v[112:113], v[114:115], v[86:87]
	v_readlane_b32 s7, v254, 21
	v_pk_add_f32 v[110:111], v[112:113], v[90:91]
	s_andn2_b64 vcc, exec, s[6:7]
	v_pk_add_f32 v[108:109], v[110:111], v[96:97]
	s_mov_b64 s[6:7], -1
	v_pk_add_f32 v[106:107], v[108:109], v[100:101]
	s_nop 0
	v_pk_add_f32 v[104:105], v[106:107], v[102:103]
	ds_write_b64 v58, v[104:105]
	v_add_u32_e32 v58, 0x20a00, v160
	s_waitcnt lgkmcnt(0)
	s_barrier
	ds_read2st64_b64 v[70:73], v58 offset1:1
	ds_read2st64_b64 v[66:69], v58 offset0:2 offset1:3
	ds_read2st64_b64 v[62:65], v58 offset0:4 offset1:5
	ds_read2st64_b64 v[58:61], v58 offset0:6 offset1:7
	s_add_i32 s8, s2, 1
	s_min_u32 s8, s8, 31
	s_lshl_b32 s8, s8, 6
	s_mov_b32 s9, s37
	s_lshl_b64 s[10:11], s[8:9], 13
	v_lshl_add_u64 v[238:239], v[76:77], 0, s[10:11]
	global_load_dwordx2 v[92:93], v[238:239], off nt
	s_add_u32 s10, s10, 0x2000
	s_addc_u32 s11, s11, 0
	v_lshl_add_u64 v[238:239], v[76:77], 0, s[10:11]
	global_load_dwordx2 v[80:81], v[238:239], off nt
	s_add_u32 s10, s10, 0x2000
	s_addc_u32 s11, s11, 0
	v_lshl_add_u64 v[238:239], v[76:77], 0, s[10:11]
	global_load_dwordx2 v[82:83], v[238:239], off nt
	s_add_u32 s10, s10, 0x2000
	s_addc_u32 s11, s11, 0
	v_lshl_add_u64 v[238:239], v[76:77], 0, s[10:11]
	global_load_dwordx2 v[86:87], v[238:239], off nt
	s_add_u32 s10, s10, 0x2000
	s_addc_u32 s11, s11, 0
	v_lshl_add_u64 v[238:239], v[76:77], 0, s[10:11]
	global_load_dwordx2 v[90:91], v[238:239], off nt
	s_add_u32 s10, s10, 0x2000
	s_addc_u32 s11, s11, 0
	v_lshl_add_u64 v[238:239], v[76:77], 0, s[10:11]
	global_load_dwordx2 v[96:97], v[238:239], off nt
	s_add_u32 s10, s10, 0x2000
	s_addc_u32 s11, s11, 0
	v_lshl_add_u64 v[238:239], v[76:77], 0, s[10:11]
	global_load_dwordx2 v[100:101], v[238:239], off nt
	s_add_u32 s10, s10, 0x2000
	s_addc_u32 s11, s11, 0
	v_lshl_add_u64 v[238:239], v[76:77], 0, s[10:11]
	global_load_dwordx2 v[102:103], v[238:239], off nt
	s_waitcnt lgkmcnt(3)
	v_pk_add_f32 v[122:123], v[70:71], 0 op_sel_hi:[1,0]
	s_nop 0
	v_pk_add_f32 v[70:71], v[122:123], v[72:73]
	s_waitcnt lgkmcnt(2)
	v_pk_add_f32 v[70:71], v[70:71], v[66:67]
	s_nop 0
	v_pk_add_f32 v[70:71], v[70:71], v[68:69]
	s_waitcnt lgkmcnt(1)
	v_pk_add_f32 v[120:121], v[70:71], v[62:63]
	s_nop 0
	v_pk_add_f32 v[120:121], v[120:121], v[64:65]
	s_waitcnt lgkmcnt(0)
	v_pk_add_f32 v[120:121], v[120:121], v[58:59]
	s_nop 0
	v_pk_add_f32 v[120:121], v[120:121], v[60:61]
	s_cbranch_vccnz .LBB0_1171
	s_mov_b64 s[6:7], 0

.LBB0_1173:
	v_readlane_b32 s6, v254, 18
	v_readlane_b32 s7, v254, 19
	s_mul_i32 s3, s20, 0x880
	s_nop 0
	v_cndmask_b32_e64 v123, v123, 0, s[6:7]
	v_cndmask_b32_e64 v122, v122, 0, s[6:7]
	v_readlane_b32 s6, v254, 26
	v_pk_add_f32 v[72:73], v[72:73], v[122:123]
	v_readlane_b32 s7, v254, 27
	s_nop 1
	v_cndmask_b32_e64 v73, v123, v73, s[6:7]
	v_cndmask_b32_e64 v72, v122, v72, s[6:7]
	v_readlane_b32 s6, v254, 28
	v_pk_add_f32 v[66:67], v[66:67], v[72:73]
	v_readlane_b32 s7, v254, 29
	s_nop 1
	v_cndmask_b32_e64 v67, v73, v67, s[6:7]
	v_cndmask_b32_e64 v66, v72, v66, s[6:7]
	v_readlane_b32 s6, v254, 30
	v_pk_add_f32 v[68:69], v[68:69], v[66:67]
	v_readlane_b32 s7, v254, 31
	s_nop 1
	v_cndmask_b32_e64 v67, v67, v69, s[6:7]
	v_cndmask_b32_e64 v66, v66, v68, s[6:7]
	v_readlane_b32 s6, v254, 32
	v_pk_add_f32 v[62:63], v[62:63], v[66:67]
	v_readlane_b32 s7, v254, 33
	v_and_b32_e32 v69, 0xffff0000, v125
	v_lshlrev_b32_e32 v68, 16, v125
	v_cndmask_b32_e64 v63, v67, v63, s[6:7]
	v_cndmask_b32_e64 v62, v66, v62, s[6:7]
	v_readlane_b32 s6, v254, 34
	v_pk_add_f32 v[64:65], v[64:65], v[62:63]
	v_readlane_b32 s7, v254, 35
	v_lshlrev_b32_e32 v66, 16, v75
	v_and_b32_e32 v67, 0xffff0000, v75
	s_mov_b32 s10, s8
	s_mul_i32 s10, s10, 0x6000
	s_mov_b32 s11, 0
	v_lshl_add_u64 v[238:239], v[78:79], 0, s[10:11]
	global_load_dword v75, v[238:239], off nt
	s_add_u32 s10, s10, 0x1000
	v_lshl_add_u64 v[240:241], v[78:79], 0, s[10:11]
	global_load_dword v125, v[240:241], off nt
	v_cndmask_b32_e64 v63, v63, v65, s[6:7]
	v_cndmask_b32_e64 v62, v62, v64, s[6:7]
	v_readlane_b32 s6, v254, 36
	v_pk_add_f32 v[58:59], v[58:59], v[62:63]
	v_readlane_b32 s7, v254, 37
	s_nop 1
	v_cndmask_b32_e64 v59, v63, v59, s[6:7]
	v_cndmask_b32_e64 v58, v62, v58, s[6:7]
	v_readlane_b32 s6, v254, 40
	v_pk_add_f32 v[60:61], v[60:61], v[58:59]
	v_readlane_b32 s7, v254, 41
	s_nop 1
	v_cndmask_b32_e64 v58, v58, v60, s[6:7]
	v_sub_f32_e32 v60, v120, v70
	v_cndmask_b32_e64 v59, v59, v61, s[6:7]
	v_exp_f32_e32 v64, v60
	v_sub_f32_e32 v60, v121, v71
	v_exp_f32_e32 v65, v60
	v_pk_add_f32 v[60:61], v[118:119], v[58:59]
	s_nop 0
	v_pk_add_f32 v[62:63], v[60:61], v[70:71] neg_lo:[0,1] neg_hi:[0,1]
	v_exp_f32_e32 v60, v60
	v_min_f32_e32 v73, 0x42e60000, v63
	v_min_f32_e64 v63, -v63, s14
	v_min_f32_e32 v72, 0x42e60000, v62
	v_min_f32_e64 v62, -v62, s14
	v_exp_f32_e32 v63, v63
	v_exp_f32_e32 v72, v72
	v_exp_f32_e32 v73, v73
	v_exp_f32_e32 v62, v62
	v_exp_f32_e32 v61, v61
	v_mul_f32_e32 v63, v63, v69
	v_add_u32_e32 v69, s3, v0
	v_mul_f32_e32 v60, v60, v66
	v_mul_f32_e32 v72, v72, v66
	v_mul_f32_e32 v73, v73, v67
	v_mul_f32_e32 v62, v62, v68
	v_cvt_pk_bf16_f32 v68, v72, v73
	ds_write_b32 v69, v68
	v_mul_f32_e32 v61, v61, v67
	v_cvt_pk_bf16_f32 v60, v60, v61
	ds_write_b32 v69, v60 offset:17408
	v_cvt_pk_bf16_f32 v60, v62, v63
	ds_write_b32 v69, v60 offset:34816
	v_pk_add_f32 v[60:61], v[116:117], v[58:59]
	v_mul_f32_e32 v66, v64, v62
	v_mul_f32_e32 v67, v63, v65
	v_pk_add_f32 v[62:63], v[60:61], v[70:71] neg_lo:[0,1] neg_hi:[0,1]
	v_exp_f32_e32 v60, v60
	v_min_f32_e32 v117, 0x42e60000, v62
	v_min_f32_e32 v118, 0x42e60000, v63
	v_min_f32_e64 v62, -v62, s14
	v_exp_f32_e32 v117, v117
	v_exp_f32_e32 v118, v118
	v_exp_f32_e32 v62, v62
	v_min_f32_e64 v63, -v63, s14
	v_exp_f32_e32 v61, v61
	v_exp_f32_e32 v63, v63
	v_lshlrev_b32_e32 v68, 16, v126
	v_and_b32_e32 v72, 0xffff0000, v126
	v_lshlrev_b32_e32 v73, 16, v127
	v_mul_f32_e32 v60, v60, v68
	v_and_b32_e32 v116, 0xffff0000, v127
	s_or_b32 s10, s8, 1
	s_mul_i32 s10, s10, 0x6000
	s_mov_b32 s11, 0
	v_lshl_add_u64 v[238:239], v[78:79], 0, s[10:11]
	global_load_dword v126, v[238:239], off nt
	s_add_u32 s10, s10, 0x1000
	v_lshl_add_u64 v[240:241], v[78:79], 0, s[10:11]
	global_load_dword v127, v[240:241], off nt
	v_mul_f32_e32 v117, v117, v68
	v_mul_f32_e32 v118, v118, v72
	v_mul_f32_e32 v62, v62, v73
	v_cvt_pk_bf16_f32 v73, v117, v118
	ds_write_b32 v69, v73 offset:272
	v_mul_f32_e32 v61, v61, v72
	v_cvt_pk_bf16_f32 v60, v60, v61
	v_mul_f32_e32 v63, v63, v116
	ds_write_b32 v69, v60 offset:17680
	v_cvt_pk_bf16_f32 v60, v62, v63
	ds_write_b32 v69, v60 offset:35088
	v_pk_add_f32 v[60:61], v[114:115], v[58:59]
	v_mul_f32_e32 v68, v64, v62
	v_mul_f32_e32 v72, v63, v65
	v_pk_add_f32 v[62:63], v[60:61], v[70:71] neg_lo:[0,1] neg_hi:[0,1]
	v_exp_f32_e32 v60, v60
	v_min_f32_e32 v117, 0x42e60000, v62
	v_min_f32_e32 v118, 0x42e60000, v63
	v_min_f32_e64 v62, -v62, s14
	v_exp_f32_e32 v117, v117
	v_exp_f32_e32 v118, v118
	v_exp_f32_e32 v62, v62
	v_min_f32_e64 v63, -v63, s14
	v_exp_f32_e32 v61, v61
	v_exp_f32_e32 v63, v63
	v_lshlrev_b32_e32 v73, 16, v128
	v_and_b32_e32 v114, 0xffff0000, v128
	v_lshlrev_b32_e32 v115, 16, v129
	v_mul_f32_e32 v60, v60, v73
	v_and_b32_e32 v116, 0xffff0000, v129
	s_or_b32 s10, s8, 2
	s_mul_i32 s10, s10, 0x6000
	s_mov_b32 s11, 0
	v_lshl_add_u64 v[238:239], v[78:79], 0, s[10:11]
	global_load_dword v128, v[238:239], off nt
	s_add_u32 s10, s10, 0x1000
	v_lshl_add_u64 v[240:241], v[78:79], 0, s[10:11]
	global_load_dword v129, v[240:241], off nt
	v_mul_f32_e32 v117, v117, v73
	v_mul_f32_e32 v118, v118, v114
	v_mul_f32_e32 v62, v62, v115
	v_cvt_pk_bf16_f32 v115, v117, v118
	ds_write_b32 v69, v115 offset:544
	v_mul_f32_e32 v61, v61, v114
	v_cvt_pk_bf16_f32 v60, v60, v61
	v_mul_f32_e32 v63, v63, v116
	ds_write_b32 v69, v60 offset:17952
	v_cvt_pk_bf16_f32 v60, v62, v63
	ds_write_b32 v69, v60 offset:35360
	v_pk_add_f32 v[60:61], v[112:113], v[58:59]
	v_mul_f32_e32 v73, v64, v62
	v_mul_f32_e32 v114, v63, v65
	v_pk_add_f32 v[62:63], v[60:61], v[70:71] neg_lo:[0,1] neg_hi:[0,1]
	v_exp_f32_e32 v60, v60
	v_min_f32_e32 v117, 0x42e60000, v62
	v_min_f32_e32 v118, 0x42e60000, v63
	v_min_f32_e64 v62, -v62, s14
	v_exp_f32_e32 v117, v117
	v_exp_f32_e32 v118, v118
	v_exp_f32_e32 v62, v62
	v_min_f32_e64 v63, -v63, s14
	v_exp_f32_e32 v61, v61
	v_exp_f32_e32 v63, v63
	v_lshlrev_b32_e32 v112, 16, v130
	v_and_b32_e32 v113, 0xffff0000, v130
	v_lshlrev_b32_e32 v115, 16, v131
	v_mul_f32_e32 v60, v60, v112
	v_and_b32_e32 v116, 0xffff0000, v131
	s_or_b32 s10, s8, 3
	s_mul_i32 s10, s10, 0x6000
	s_mov_b32 s11, 0
	v_lshl_add_u64 v[238:239], v[78:79], 0, s[10:11]
	global_load_dword v130, v[238:239], off nt
	s_add_u32 s10, s10, 0x1000
	v_lshl_add_u64 v[240:241], v[78:79], 0, s[10:11]
	global_load_dword v131, v[240:241], off nt
	v_mul_f32_e32 v117, v117, v112
	v_mul_f32_e32 v118, v118, v113
	v_mul_f32_e32 v62, v62, v115
	v_cvt_pk_bf16_f32 v115, v117, v118
	ds_write_b32 v69, v115 offset:816
	v_mul_f32_e32 v61, v61, v113
	v_cvt_pk_bf16_f32 v60, v60, v61
	v_mul_f32_e32 v63, v63, v116
	ds_write_b32 v69, v60 offset:18224
	v_cvt_pk_bf16_f32 v60, v62, v63
	ds_write_b32 v69, v60 offset:35632
	v_pk_add_f32 v[60:61], v[110:111], v[58:59]
	v_mul_f32_e32 v112, v64, v62
	v_mul_f32_e32 v113, v63, v65
	v_pk_add_f32 v[62:63], v[60:61], v[70:71] neg_lo:[0,1] neg_hi:[0,1]
	v_exp_f32_e32 v60, v60
	v_min_f32_e32 v117, 0x42e60000, v62
	v_min_f32_e32 v118, 0x42e60000, v63
	v_min_f32_e64 v62, -v62, s14
	v_exp_f32_e32 v117, v117
	v_exp_f32_e32 v118, v118
	v_exp_f32_e32 v62, v62
	v_min_f32_e64 v63, -v63, s14
	v_exp_f32_e32 v61, v61
	v_exp_f32_e32 v63, v63
	v_lshlrev_b32_e32 v110, 16, v140
	v_and_b32_e32 v111, 0xffff0000, v140
	v_lshlrev_b32_e32 v115, 16, v142
	v_mul_f32_e32 v60, v60, v110
	v_and_b32_e32 v116, 0xffff0000, v142
	s_or_b32 s10, s8, 4
	s_mul_i32 s10, s10, 0x6000
	s_mov_b32 s11, 0
	v_lshl_add_u64 v[238:239], v[78:79], 0, s[10:11]
	global_load_dword v140, v[238:239], off nt
	s_add_u32 s10, s10, 0x1000
	v_lshl_add_u64 v[240:241], v[78:79], 0, s[10:11]
	global_load_dword v142, v[240:241], off nt
	v_mul_f32_e32 v117, v117, v110
	v_mul_f32_e32 v118, v118, v111
	v_mul_f32_e32 v62, v62, v115
	v_cvt_pk_bf16_f32 v115, v117, v118
	ds_write_b32 v69, v115 offset:1088
	v_mul_f32_e32 v61, v61, v111
	v_cvt_pk_bf16_f32 v60, v60, v61
	v_mul_f32_e32 v63, v63, v116
	ds_write_b32 v69, v60 offset:18496
	v_cvt_pk_bf16_f32 v60, v62, v63
	ds_write_b32 v69, v60 offset:35904
	v_pk_add_f32 v[60:61], v[108:109], v[58:59]
	v_mul_f32_e32 v110, v64, v62
	v_mul_f32_e32 v111, v63, v65
	v_pk_add_f32 v[62:63], v[60:61], v[70:71] neg_lo:[0,1] neg_hi:[0,1]
	v_exp_f32_e32 v60, v60
	v_min_f32_e32 v117, 0x42e60000, v62
	v_min_f32_e32 v118, 0x42e60000, v63
	v_min_f32_e64 v62, -v62, s14
	v_exp_f32_e32 v117, v117
	v_exp_f32_e32 v118, v118
	v_exp_f32_e32 v62, v62
	v_min_f32_e64 v63, -v63, s14
	v_exp_f32_e32 v61, v61
	v_exp_f32_e32 v63, v63
	v_lshlrev_b32_e32 v108, 16, v144
	v_and_b32_e32 v109, 0xffff0000, v144
	v_lshlrev_b32_e32 v115, 16, v149
	v_mul_f32_e32 v60, v60, v108
	v_and_b32_e32 v116, 0xffff0000, v149
	s_or_b32 s10, s8, 5
	s_mul_i32 s10, s10, 0x6000
	s_mov_b32 s11, 0
	v_lshl_add_u64 v[238:239], v[78:79], 0, s[10:11]
	global_load_dword v144, v[238:239], off nt
	s_add_u32 s10, s10, 0x1000
	v_lshl_add_u64 v[240:241], v[78:79], 0, s[10:11]
	global_load_dword v149, v[240:241], off nt
	v_mul_f32_e32 v117, v117, v108
	v_mul_f32_e32 v118, v118, v109
	v_mul_f32_e32 v62, v62, v115
	v_cvt_pk_bf16_f32 v115, v117, v118
	ds_write_b32 v69, v115 offset:1360
	v_mul_f32_e32 v61, v61, v109
	v_cvt_pk_bf16_f32 v60, v60, v61
	v_mul_f32_e32 v63, v63, v116
	ds_write_b32 v69, v60 offset:18768
	v_cvt_pk_bf16_f32 v60, v62, v63
	ds_write_b32 v69, v60 offset:36176
	v_pk_add_f32 v[60:61], v[106:107], v[58:59]
	v_mul_f32_e32 v108, v64, v62
	v_mul_f32_e32 v109, v63, v65
	v_pk_add_f32 v[62:63], v[60:61], v[70:71] neg_lo:[0,1] neg_hi:[0,1]
	v_exp_f32_e32 v60, v60
	v_min_f32_e32 v117, 0x42e60000, v62
	v_min_f32_e32 v118, 0x42e60000, v63
	v_min_f32_e64 v62, -v62, s14
	v_exp_f32_e32 v117, v117
	v_exp_f32_e32 v118, v118
	v_exp_f32_e32 v62, v62
	v_min_f32_e64 v63, -v63, s14
	v_exp_f32_e32 v61, v61
	v_exp_f32_e32 v63, v63
	v_lshlrev_b32_e32 v106, 16, v156
	v_and_b32_e32 v107, 0xffff0000, v156
	v_lshlrev_b32_e32 v115, 16, v157
	v_mul_f32_e32 v60, v60, v106
	v_and_b32_e32 v116, 0xffff0000, v157
	s_or_b32 s10, s8, 6
	s_mul_i32 s10, s10, 0x6000
	s_mov_b32 s11, 0
	v_lshl_add_u64 v[238:239], v[78:79], 0, s[10:11]
	global_load_dword v156, v[238:239], off nt
	s_add_u32 s10, s10, 0x1000
	v_lshl_add_u64 v[240:241], v[78:79], 0, s[10:11]
	global_load_dword v157, v[240:241], off nt
	v_mul_f32_e32 v117, v117, v106
	v_mul_f32_e32 v118, v118, v107
	v_mul_f32_e32 v62, v62, v115
	v_cvt_pk_bf16_f32 v115, v117, v118
	ds_write_b32 v69, v115 offset:1632
	v_mul_f32_e32 v61, v61, v107
	v_cvt_pk_bf16_f32 v60, v60, v61
	v_mul_f32_e32 v63, v63, v116
	ds_write_b32 v69, v60 offset:19040
	v_cvt_pk_bf16_f32 v60, v62, v63
	v_pk_add_f32 v[58:59], v[104:105], v[58:59]
	ds_write_b32 v69, v60 offset:36448
	v_pk_add_f32 v[60:61], v[58:59], v[70:71] neg_lo:[0,1] neg_hi:[0,1]
	v_exp_f32_e32 v58, v58
	v_min_f32_e32 v106, 0x42e60000, v60
	v_min_f32_e32 v107, 0x42e60000, v61
	v_min_f32_e64 v60, -v60, s14
	v_exp_f32_e32 v106, v106
	v_exp_f32_e32 v107, v107
	v_exp_f32_e32 v60, v60
	v_min_f32_e64 v61, -v61, s14
	v_exp_f32_e32 v59, v59
	v_exp_f32_e32 v61, v61
	v_lshlrev_b32_e32 v70, 16, v158
	v_and_b32_e32 v71, 0xffff0000, v158
	v_lshlrev_b32_e32 v104, 16, v159
	v_mul_f32_e32 v58, v58, v70
	v_and_b32_e32 v105, 0xffff0000, v159
	s_or_b32 s10, s8, 7
	s_mul_i32 s10, s10, 0x6000
	s_mov_b32 s11, 0
	v_lshl_add_u64 v[238:239], v[78:79], 0, s[10:11]
	global_load_dword v158, v[238:239], off nt
	s_add_u32 s10, s10, 0x1000
	v_lshl_add_u64 v[240:241], v[78:79], 0, s[10:11]
	global_load_dword v159, v[240:241], off nt
	v_mul_f32_e32 v106, v106, v70
	v_mul_f32_e32 v107, v107, v71
	v_mul_f32_e32 v60, v60, v104
	v_cvt_pk_bf16_f32 v104, v106, v107
	ds_write_b32 v69, v104 offset:1904
	v_mul_f32_e32 v59, v59, v71
	v_cvt_pk_bf16_f32 v58, v58, v59
	v_mul_f32_e32 v61, v61, v105
	ds_write_b32 v69, v58 offset:19312
	v_cvt_pk_bf16_f32 v58, v60, v61
	ds_write_b32 v69, v58 offset:36720
	v_cvt_pk_bf16_f32 v58, v66, v68
	v_mul_f32_e32 v62, v64, v62
	v_mul_f32_e32 v63, v63, v65
	v_mul_f32_e32 v64, v64, v60
	v_mul_f32_e32 v65, v61, v65
	v_cvt_pk_bf16_f32 v59, v73, v112
	v_cvt_pk_bf16_f32 v60, v110, v108
	v_cvt_pk_bf16_f32 v61, v62, v64
	ds_write_b128 v143, v[58:61] offset:52224
	v_cvt_pk_bf16_f32 v58, v67, v72
	s_add_i32 s3, s2, 1
	v_cvt_pk_bf16_f32 v59, v114, v113
	v_cvt_pk_bf16_f32 v60, v111, v109
	v_cvt_pk_bf16_f32 v61, v63, v65
	ds_write_b128 v143, v[58:61] offset:52368
	v_add_u32_e32 v58, s19, v74
	s_cmp_eq_u32 s2, 31
	ds_write_b16 v58, v22
	ds_write_b16_d16_hi v58, v22 offset:144
	ds_write_b16 v58, v23 offset:288
	ds_write_b16_d16_hi v58, v23 offset:432
	ds_write_b16 v58, v24 offset:576
	ds_write_b16_d16_hi v58, v24 offset:720
	ds_write_b16 v58, v25 offset:864
	ds_write_b16_d16_hi v58, v25 offset:1008
	s_waitcnt vmcnt(28)
	ds_write_b16 v58, v26 offset:1152
	ds_write_b16_d16_hi v58, v26 offset:1296
	ds_write_b16 v58, v27 offset:1440
	ds_write_b16_d16_hi v58, v27 offset:1584
	ds_write_b16 v58, v28 offset:1728
	ds_write_b16_d16_hi v58, v28 offset:1872
	ds_write_b16 v58, v29 offset:2016
	ds_write_b16_d16_hi v58, v29 offset:2160
	s_cbranch_scc1 .LBB0_1175
	s_mul_i32 s6, s3, 0x180000
	s_mov_b32 s7, s37
	v_lshl_add_u64 v[26:27], v[84:85], 0, s[6:7]
	global_load_dwordx4 v[22:25], v[26:27], off
	s_nop 0
	global_load_dwordx4 v[26:29], v[26:27], off offset:16
